# grid barrier: three release polls in flight (vmcnt(2) in the spin loop) instead of one round trip per poll
# baseline (speedup 1.0000x reference)
; __device__ __forceinline__ unsigned xb_ld(unsigned* p)              { return __hip_atomic_load(p, __ATOMIC_RELAXED, __HIP_MEMORY_SCOPE_AGENT); }
; __device__ __forceinline__ unsigned xb_add(unsigned* p, unsigned v) { return __hip_atomic_fetch_add(p, v, __ATOMIC_RELAXED, __HIP_MEMORY_SCOPE_AGENT); }
; #define XB_SPIN(cond, bar) do { unsigned _sp = 0; while (cond) { __builtin_amdgcn_s_sleep(1); \
;     if ((++_sp & 255u) == 0u) { if (xb_ld(&(bar)[XB_TMO])) break; if (_sp > XB_SPIN_CAP) { atomicAdd(&(bar)[XB_TMO], 1u); break; } } } } while (0)
; __device__ __forceinline__ void xcd_barrier(const XcdBarrier& b) {
;     ...
;         unsigned nloc = b.st[0], nx = b.st[1];
;         if (nloc == 0u) { xcd_barrier_complete(bar, b.x, nloc, nx); b.st[0] = nloc; b.st[1] = nx; }
;         const unsigned old = xb_add(&bar[XB_XSUB(b.x)], 1u);
;         const unsigned gen = old / nloc;
;         if (old + 1u == (gen + 1u) * nloc) {
;             __builtin_amdgcn_fence(__ATOMIC_RELEASE, "agent");
;             asm volatile("s_waitcnt vmcnt(0)" ::: "memory");
;             const unsigned og = xb_add(&bar[XB_TOP], 1u);
;             const unsigned tg = og / nx;
;             if (og + 1u == (tg + 1u) * nx) xb_add(&bar[XB_TOPGEN], 1u);
;             else XB_SPIN(xb_ld(&bar[XB_TOPGEN]) == tg, bar);
;             __builtin_amdgcn_fence(__ATOMIC_ACQUIRE, "agent");
;             xb_add(&bar[XB_XGEN(b.x)], 1u);
;             asm volatile("s_waitcnt vmcnt(0)" ::: "memory");
;         } else {
;             XB_SPIN(xb_ld(&bar[XB_XGEN(b.x)]) == gen, bar);
.LBB0_63:
	s_or_b64 exec, exec, s[12:13]
	v_cvt_f32_u32_e32 v5, v3
	s_waitcnt vmcnt(0)
	v_readfirstlane_b32 s0, v4
	v_sub_u32_e32 v4, 0, v3
	v_rcp_iflag_f32_e32 v5, v5
	v_add_u32_e32 v6, s0, v2
	v_mul_f32_e32 v5, 0x4f7ffffe, v5
	v_cvt_u32_f32_e32 v5, v5
	v_mul_lo_u32 v2, v4, v5
	v_mul_hi_u32 v2, v5, v2
	v_add_u32_e32 v2, v5, v2
	v_mul_hi_u32 v2, v6, v2
	v_mul_lo_u32 v4, v2, v3
	v_sub_u32_e32 v4, v6, v4
	v_add_u32_e32 v5, 1, v2
	v_cmp_ge_u32_e32 vcc, v4, v3
	s_nop 1
	v_cndmask_b32_e32 v2, v2, v5, vcc
	v_sub_u32_e32 v5, v4, v3
	v_cndmask_b32_e32 v4, v4, v5, vcc
	v_add_u32_e32 v5, 1, v2
	v_cmp_ge_u32_e32 vcc, v4, v3
	v_add_u32_e32 v4, 1, v6
	s_nop 0
	v_cndmask_b32_e32 v2, v2, v5, vcc
	v_mul_lo_u32 v5, v3, v2
	v_add_u32_e32 v3, v5, v3
	v_cmp_ne_u32_e32 vcc, v4, v3
	s_and_saveexec_b64 s[0:1], vcc
	s_xor_b64 s[18:19], exec, s[0:1]
	s_cbranch_execz .LBB0_77
	s_waitcnt lgkmcnt(0)
	buffer_inv sc1
	v_mov_b32_e32 v1, 0x2000
	global_load_dword v1, v1, s[14:15] offset:1024 sc1
	s_add_u32 s22, s14, 0x2400
	s_addc_u32 s23, s15, 0
	s_waitcnt vmcnt(0)
	v_cmp_eq_u32_e32 vcc, v1, v2
	s_and_saveexec_b64 s[0:1], vcc
	s_cbranch_execz .LBB0_76
	s_add_u32 s12, s78, 0x4200
	s_addc_u32 s13, s79, 0
	s_mov_b32 s3, 1
	s_mov_b64 s[24:25], 0
	v_mov_b32_e32 v1, 0
	global_load_dword v241, v1, s[22:23] sc1
	global_load_dword v241, v1, s[22:23] sc1
	s_branch .LBB0_67

; __device__ __forceinline__ unsigned xb_ld(unsigned* p)              { return __hip_atomic_load(p, __ATOMIC_RELAXED, __HIP_MEMORY_SCOPE_AGENT); }
; #define XB_SPIN(cond, bar) do { unsigned _sp = 0; while (cond) { __builtin_amdgcn_s_sleep(1); \
;     if ((++_sp & 255u) == 0u) { if (xb_ld(&(bar)[XB_TMO])) break; if (_sp > XB_SPIN_CAP) { atomicAdd(&(bar)[XB_TMO], 1u); break; } } } } while (0)
; __device__ __forceinline__ void xcd_barrier(const XcdBarrier& b) {
;     ...
;             XB_SPIN(xb_ld(&bar[XB_XGEN(b.x)]) == gen, bar);
.LBB0_71:
	global_load_dword v241, v1, s[22:23] sc1
	s_add_i32 s3, s3, 1
	s_mov_b64 s[68:69], -1
	s_waitcnt vmcnt(2)
	v_cmp_ne_u32_e32 vcc, v241, v2
	s_orn2_b64 s[34:35], vcc, exec
	s_branch .LBB0_66

; __device__ __forceinline__ unsigned xb_ld(unsigned* p)              { return __hip_atomic_load(p, __ATOMIC_RELAXED, __HIP_MEMORY_SCOPE_AGENT); }
; __device__ __forceinline__ unsigned xb_add(unsigned* p, unsigned v) { return __hip_atomic_fetch_add(p, v, __ATOMIC_RELAXED, __HIP_MEMORY_SCOPE_AGENT); }
; #define XB_SPIN(cond, bar) do { unsigned _sp = 0; while (cond) { __builtin_amdgcn_s_sleep(1); \
;     if ((++_sp & 255u) == 0u) { if (xb_ld(&(bar)[XB_TMO])) break; if (_sp > XB_SPIN_CAP) { atomicAdd(&(bar)[XB_TMO], 1u); break; } } } } while (0)
; __device__ __forceinline__ void xcd_barrier(const XcdBarrier& b) {
;     ...
;             const unsigned og = xb_add(&bar[XB_TOP], 1u);
;             const unsigned tg = og / nx;
;             if (og + 1u == (tg + 1u) * nx) xb_add(&bar[XB_TOPGEN], 1u);
;             else XB_SPIN(xb_ld(&bar[XB_TOPGEN]) == tg, bar);
.LBB0_80:
	s_or_b64 exec, exec, s[12:13]
	v_cvt_f32_u32_e32 v4, v1
	s_waitcnt vmcnt(0)
	v_readfirstlane_b32 s0, v3
	s_add_u32 s12, s78, 0x7500
	s_addc_u32 s13, s79, 0
	v_rcp_iflag_f32_e32 v4, v4
	v_add_u32_e32 v2, s0, v2
	v_add_u32_e32 v5, 1, v2
	s_mov_b64 s[18:19], -1
	v_mul_f32_e32 v3, 0x4f7ffffe, v4
	v_cvt_u32_f32_e32 v3, v3
	v_sub_u32_e32 v4, 0, v1
	v_mul_lo_u32 v4, v4, v3
	v_mul_hi_u32 v4, v3, v4
	v_add_u32_e32 v3, v3, v4
	v_mul_hi_u32 v3, v2, v3
	v_mul_lo_u32 v4, v3, v1
	v_sub_u32_e32 v2, v2, v4
	v_add_u32_e32 v6, 1, v3
	v_cmp_ge_u32_e32 vcc, v2, v1
	v_sub_u32_e32 v4, v2, v1
	s_nop 0
	v_cndmask_b32_e32 v3, v3, v6, vcc
	v_cndmask_b32_e32 v2, v2, v4, vcc
	v_add_u32_e32 v4, 1, v3
	v_cmp_ge_u32_e32 vcc, v2, v1
	s_nop 1
	v_cndmask_b32_e32 v4, v3, v4, vcc
	v_mul_lo_u32 v2, v1, v4
	v_add_u32_e32 v1, v2, v1
	v_cmp_ne_u32_e32 vcc, v5, v1
	v_mov_b64_e32 v[2:3], s[12:13]
	s_and_saveexec_b64 s[0:1], vcc
	s_cbranch_execz .LBB0_92
	v_mov_b32_e32 v1, 0
	global_load_dword v2, v1, s[12:13] sc1
	s_mov_b64 s[24:25], 0
	s_waitcnt vmcnt(0)
	v_cmp_eq_u32_e32 vcc, v2, v4
	s_and_saveexec_b64 s[22:23], vcc
	s_cbranch_execz .LBB0_91
	s_add_u32 s18, s78, 0x4200
	s_addc_u32 s19, s79, 0
	s_mov_b32 s3, 1
	global_load_dword v242, v1, s[12:13] sc1
	global_load_dword v242, v1, s[12:13] sc1
	s_branch .LBB0_84

; __device__ __forceinline__ unsigned xb_ld(unsigned* p)              { return __hip_atomic_load(p, __ATOMIC_RELAXED, __HIP_MEMORY_SCOPE_AGENT); }
; #define XB_SPIN(cond, bar) do { unsigned _sp = 0; while (cond) { __builtin_amdgcn_s_sleep(1); \
;     if ((++_sp & 255u) == 0u) { if (xb_ld(&(bar)[XB_TMO])) break; if (_sp > XB_SPIN_CAP) { atomicAdd(&(bar)[XB_TMO], 1u); break; } } } } while (0)
; __device__ __forceinline__ void xcd_barrier(const XcdBarrier& b) {
;     ...
;             else XB_SPIN(xb_ld(&bar[XB_TOPGEN]) == tg, bar);
.LBB0_88:
	global_load_dword v242, v1, s[12:13] sc1
	s_add_i32 s3, s3, 1
	s_mov_b64 s[34:35], -1
	s_waitcnt vmcnt(2)
	v_cmp_ne_u32_e32 vcc, v242, v4
	s_orn2_b64 s[70:71], vcc, exec
	s_branch .LBB0_83

; __device__ __forceinline__ unsigned xb_ld(unsigned* p)              { return __hip_atomic_load(p, __ATOMIC_RELAXED, __HIP_MEMORY_SCOPE_AGENT); }
; __device__ __forceinline__ unsigned xb_add(unsigned* p, unsigned v) { return __hip_atomic_fetch_add(p, v, __ATOMIC_RELAXED, __HIP_MEMORY_SCOPE_AGENT); }
; #define XB_SPIN(cond, bar) do { unsigned _sp = 0; while (cond) { __builtin_amdgcn_s_sleep(1); \
;     if ((++_sp & 255u) == 0u) { if (xb_ld(&(bar)[XB_TMO])) break; if (_sp > XB_SPIN_CAP) { atomicAdd(&(bar)[XB_TMO], 1u); break; } } } } while (0)
; __device__ __forceinline__ void xcd_barrier(const XcdBarrier& b) {
;     ...
;         unsigned nloc = b.st[0], nx = b.st[1];
;         if (nloc == 0u) { xcd_barrier_complete(bar, b.x, nloc, nx); b.st[0] = nloc; b.st[1] = nx; }
;         const unsigned old = xb_add(&bar[XB_XSUB(b.x)], 1u);
;         const unsigned gen = old / nloc;
;         if (old + 1u == (gen + 1u) * nloc) {
;             __builtin_amdgcn_fence(__ATOMIC_RELEASE, "agent");
;             asm volatile("s_waitcnt vmcnt(0)" ::: "memory");
;             const unsigned og = xb_add(&bar[XB_TOP], 1u);
;             const unsigned tg = og / nx;
;             if (og + 1u == (tg + 1u) * nx) xb_add(&bar[XB_TOPGEN], 1u);
;             else XB_SPIN(xb_ld(&bar[XB_TOPGEN]) == tg, bar);
;             __builtin_amdgcn_fence(__ATOMIC_ACQUIRE, "agent");
;             xb_add(&bar[XB_XGEN(b.x)], 1u);
;             asm volatile("s_waitcnt vmcnt(0)" ::: "memory");
;         } else {
;             XB_SPIN(xb_ld(&bar[XB_XGEN(b.x)]) == gen, bar);
.LBB0_217:
	s_or_b64 exec, exec, s[12:13]
	v_cvt_f32_u32_e32 v5, v3
	s_waitcnt vmcnt(0)
	v_readfirstlane_b32 s0, v4
	v_sub_u32_e32 v4, 0, v3
	v_rcp_iflag_f32_e32 v5, v5
	v_add_u32_e32 v6, s0, v2
	v_mul_f32_e32 v5, 0x4f7ffffe, v5
	v_cvt_u32_f32_e32 v5, v5
	v_mul_lo_u32 v2, v4, v5
	v_mul_hi_u32 v2, v5, v2
	v_add_u32_e32 v2, v5, v2
	v_mul_hi_u32 v2, v6, v2
	v_mul_lo_u32 v4, v2, v3
	v_sub_u32_e32 v4, v6, v4
	v_add_u32_e32 v5, 1, v2
	v_cmp_ge_u32_e32 vcc, v4, v3
	s_nop 1
	v_cndmask_b32_e32 v2, v2, v5, vcc
	v_sub_u32_e32 v5, v4, v3
	v_cndmask_b32_e32 v4, v4, v5, vcc
	v_add_u32_e32 v5, 1, v2
	v_cmp_ge_u32_e32 vcc, v4, v3
	v_add_u32_e32 v4, 1, v6
	s_nop 0
	v_cndmask_b32_e32 v2, v2, v5, vcc
	v_mul_lo_u32 v5, v3, v2
	v_add_u32_e32 v3, v5, v3
	v_cmp_ne_u32_e32 vcc, v4, v3
	s_and_saveexec_b64 s[0:1], vcc
	s_xor_b64 s[18:19], exec, s[0:1]
	s_cbranch_execz .LBB0_231
	s_waitcnt lgkmcnt(0)
	buffer_inv sc1
	v_mov_b32_e32 v1, 0x2000
	global_load_dword v1, v1, s[6:7] offset:1024 sc1
	s_add_u32 s20, s6, 0x2400
	s_addc_u32 s21, s7, 0
	s_waitcnt vmcnt(0)
	v_cmp_eq_u32_e32 vcc, v1, v2
	s_and_saveexec_b64 s[0:1], vcc
	s_cbranch_execz .LBB0_230
	s_add_u32 s12, s78, 0x4200
	s_addc_u32 s13, s79, 0
	s_mov_b32 s3, 1
	s_mov_b64 s[26:27], 0
	v_mov_b32_e32 v1, 0
	global_load_dword v241, v1, s[20:21] sc1
	global_load_dword v241, v1, s[20:21] sc1
	s_branch .LBB0_221

; __device__ __forceinline__ unsigned xb_ld(unsigned* p)              { return __hip_atomic_load(p, __ATOMIC_RELAXED, __HIP_MEMORY_SCOPE_AGENT); }
; #define XB_SPIN(cond, bar) do { unsigned _sp = 0; while (cond) { __builtin_amdgcn_s_sleep(1); \
;     if ((++_sp & 255u) == 0u) { if (xb_ld(&(bar)[XB_TMO])) break; if (_sp > XB_SPIN_CAP) { atomicAdd(&(bar)[XB_TMO], 1u); break; } } } } while (0)
; __device__ __forceinline__ void xcd_barrier(const XcdBarrier& b) {
;     ...
;             XB_SPIN(xb_ld(&bar[XB_XGEN(b.x)]) == gen, bar);
.LBB0_225:
	global_load_dword v241, v1, s[20:21] sc1
	s_add_i32 s3, s3, 1
	s_mov_b64 s[56:57], -1
	s_waitcnt vmcnt(2)
	v_cmp_ne_u32_e32 vcc, v241, v2
	s_orn2_b64 s[34:35], vcc, exec
	s_branch .LBB0_220

; __device__ __forceinline__ unsigned xb_ld(unsigned* p)              { return __hip_atomic_load(p, __ATOMIC_RELAXED, __HIP_MEMORY_SCOPE_AGENT); }
; __device__ __forceinline__ unsigned xb_add(unsigned* p, unsigned v) { return __hip_atomic_fetch_add(p, v, __ATOMIC_RELAXED, __HIP_MEMORY_SCOPE_AGENT); }
; #define XB_SPIN(cond, bar) do { unsigned _sp = 0; while (cond) { __builtin_amdgcn_s_sleep(1); \
;     if ((++_sp & 255u) == 0u) { if (xb_ld(&(bar)[XB_TMO])) break; if (_sp > XB_SPIN_CAP) { atomicAdd(&(bar)[XB_TMO], 1u); break; } } } } while (0)
; __device__ __forceinline__ void xcd_barrier(const XcdBarrier& b) {
;     ...
;             const unsigned og = xb_add(&bar[XB_TOP], 1u);
;             const unsigned tg = og / nx;
;             if (og + 1u == (tg + 1u) * nx) xb_add(&bar[XB_TOPGEN], 1u);
;             else XB_SPIN(xb_ld(&bar[XB_TOPGEN]) == tg, bar);
.LBB0_234:
	s_or_b64 exec, exec, s[12:13]
	v_cvt_f32_u32_e32 v4, v1
	s_waitcnt vmcnt(0)
	v_readfirstlane_b32 s0, v3
	s_add_u32 s12, s78, 0x7500
	s_addc_u32 s13, s79, 0
	v_rcp_iflag_f32_e32 v4, v4
	v_add_u32_e32 v2, s0, v2
	v_add_u32_e32 v5, 1, v2
	s_mov_b64 s[18:19], -1
	v_mul_f32_e32 v3, 0x4f7ffffe, v4
	v_cvt_u32_f32_e32 v3, v3
	v_sub_u32_e32 v4, 0, v1
	v_mul_lo_u32 v4, v4, v3
	v_mul_hi_u32 v4, v3, v4
	v_add_u32_e32 v3, v3, v4
	v_mul_hi_u32 v3, v2, v3
	v_mul_lo_u32 v4, v3, v1
	v_sub_u32_e32 v2, v2, v4
	v_add_u32_e32 v6, 1, v3
	v_cmp_ge_u32_e32 vcc, v2, v1
	v_sub_u32_e32 v4, v2, v1
	s_nop 0
	v_cndmask_b32_e32 v3, v3, v6, vcc
	v_cndmask_b32_e32 v2, v2, v4, vcc
	v_add_u32_e32 v4, 1, v3
	v_cmp_ge_u32_e32 vcc, v2, v1
	s_nop 1
	v_cndmask_b32_e32 v4, v3, v4, vcc
	v_mul_lo_u32 v2, v1, v4
	v_add_u32_e32 v1, v2, v1
	v_cmp_ne_u32_e32 vcc, v5, v1
	v_mov_b64_e32 v[2:3], s[12:13]
	s_and_saveexec_b64 s[0:1], vcc
	s_cbranch_execz .LBB0_246
	v_mov_b32_e32 v1, 0
	global_load_dword v2, v1, s[12:13] sc1
	s_mov_b64 s[26:27], 0
	s_waitcnt vmcnt(0)
	v_cmp_eq_u32_e32 vcc, v2, v4
	s_and_saveexec_b64 s[20:21], vcc
	s_cbranch_execz .LBB0_245
	s_add_u32 s18, s78, 0x4200
	s_addc_u32 s19, s79, 0
	s_mov_b32 s3, 1
	global_load_dword v242, v1, s[12:13] sc1
	global_load_dword v242, v1, s[12:13] sc1
	s_branch .LBB0_238

; __device__ __forceinline__ unsigned xb_ld(unsigned* p)              { return __hip_atomic_load(p, __ATOMIC_RELAXED, __HIP_MEMORY_SCOPE_AGENT); }
; #define XB_SPIN(cond, bar) do { unsigned _sp = 0; while (cond) { __builtin_amdgcn_s_sleep(1); \
;     if ((++_sp & 255u) == 0u) { if (xb_ld(&(bar)[XB_TMO])) break; if (_sp > XB_SPIN_CAP) { atomicAdd(&(bar)[XB_TMO], 1u); break; } } } } while (0)
; __device__ __forceinline__ void xcd_barrier(const XcdBarrier& b) {
;     ...
;             else XB_SPIN(xb_ld(&bar[XB_TOPGEN]) == tg, bar);
.LBB0_242:
	global_load_dword v242, v1, s[12:13] sc1
	s_add_i32 s3, s3, 1
	s_mov_b64 s[34:35], -1
	s_waitcnt vmcnt(2)
	v_cmp_ne_u32_e32 vcc, v242, v4
	s_orn2_b64 s[68:69], vcc, exec
	s_branch .LBB0_237

; __device__ __forceinline__ unsigned xb_ld(unsigned* p)              { return __hip_atomic_load(p, __ATOMIC_RELAXED, __HIP_MEMORY_SCOPE_AGENT); }
; __device__ __forceinline__ unsigned xb_add(unsigned* p, unsigned v) { return __hip_atomic_fetch_add(p, v, __ATOMIC_RELAXED, __HIP_MEMORY_SCOPE_AGENT); }
; #define XB_SPIN(cond, bar) do { unsigned _sp = 0; while (cond) { __builtin_amdgcn_s_sleep(1); \
;     if ((++_sp & 255u) == 0u) { if (xb_ld(&(bar)[XB_TMO])) break; if (_sp > XB_SPIN_CAP) { atomicAdd(&(bar)[XB_TMO], 1u); break; } } } } while (0)
; __device__ __forceinline__ void xcd_barrier(const XcdBarrier& b) {
;     ...
;         unsigned nloc = b.st[0], nx = b.st[1];
;         if (nloc == 0u) { xcd_barrier_complete(bar, b.x, nloc, nx); b.st[0] = nloc; b.st[1] = nx; }
;         const unsigned old = xb_add(&bar[XB_XSUB(b.x)], 1u);
;         const unsigned gen = old / nloc;
;         if (old + 1u == (gen + 1u) * nloc) {
;             __builtin_amdgcn_fence(__ATOMIC_RELEASE, "agent");
;             asm volatile("s_waitcnt vmcnt(0)" ::: "memory");
;             const unsigned og = xb_add(&bar[XB_TOP], 1u);
;             const unsigned tg = og / nx;
;             if (og + 1u == (tg + 1u) * nx) xb_add(&bar[XB_TOPGEN], 1u);
;             else XB_SPIN(xb_ld(&bar[XB_TOPGEN]) == tg, bar);
;             __builtin_amdgcn_fence(__ATOMIC_ACQUIRE, "agent");
;             xb_add(&bar[XB_XGEN(b.x)], 1u);
;             asm volatile("s_waitcnt vmcnt(0)" ::: "memory");
;         } else {
;             XB_SPIN(xb_ld(&bar[XB_XGEN(b.x)]) == gen, bar);
.LBB0_331:
	s_or_b64 exec, exec, s[12:13]
	v_cvt_f32_u32_e32 v5, v3
	s_waitcnt vmcnt(0)
	v_readfirstlane_b32 s0, v4
	v_sub_u32_e32 v4, 0, v3
	v_rcp_iflag_f32_e32 v5, v5
	v_add_u32_e32 v6, s0, v2
	v_mul_f32_e32 v5, 0x4f7ffffe, v5
	v_cvt_u32_f32_e32 v5, v5
	v_mul_lo_u32 v2, v4, v5
	v_mul_hi_u32 v2, v5, v2
	v_add_u32_e32 v2, v5, v2
	v_mul_hi_u32 v2, v6, v2
	v_mul_lo_u32 v4, v2, v3
	v_sub_u32_e32 v4, v6, v4
	v_add_u32_e32 v5, 1, v2
	v_cmp_ge_u32_e32 vcc, v4, v3
	s_nop 1
	v_cndmask_b32_e32 v2, v2, v5, vcc
	v_sub_u32_e32 v5, v4, v3
	v_cndmask_b32_e32 v4, v4, v5, vcc
	v_add_u32_e32 v5, 1, v2
	v_cmp_ge_u32_e32 vcc, v4, v3
	v_add_u32_e32 v4, 1, v6
	s_nop 0
	v_cndmask_b32_e32 v2, v2, v5, vcc
	v_mul_lo_u32 v5, v3, v2
	v_add_u32_e32 v3, v5, v3
	v_cmp_ne_u32_e32 vcc, v4, v3
	s_and_saveexec_b64 s[0:1], vcc
	s_xor_b64 s[20:21], exec, s[0:1]
	s_cbranch_execz .LBB0_345
	s_waitcnt lgkmcnt(0)
	buffer_inv sc1
	v_mov_b32_e32 v1, 0x2000
	global_load_dword v1, v1, s[6:7] offset:1024 sc1
	s_add_u32 s26, s6, 0x2400
	s_addc_u32 s27, s7, 0
	s_waitcnt vmcnt(0)
	v_cmp_eq_u32_e32 vcc, v1, v2
	s_and_saveexec_b64 s[0:1], vcc
	s_cbranch_execz .LBB0_344
	s_add_u32 s12, s78, 0x4200
	s_addc_u32 s13, s79, 0
	s_mov_b32 s3, 1
	s_mov_b64 s[28:29], 0
	v_mov_b32_e32 v1, 0
	global_load_dword v241, v1, s[26:27] sc1
	global_load_dword v241, v1, s[26:27] sc1
	s_branch .LBB0_335

; __device__ __forceinline__ unsigned xb_ld(unsigned* p)              { return __hip_atomic_load(p, __ATOMIC_RELAXED, __HIP_MEMORY_SCOPE_AGENT); }
; #define XB_SPIN(cond, bar) do { unsigned _sp = 0; while (cond) { __builtin_amdgcn_s_sleep(1); \
;     if ((++_sp & 255u) == 0u) { if (xb_ld(&(bar)[XB_TMO])) break; if (_sp > XB_SPIN_CAP) { atomicAdd(&(bar)[XB_TMO], 1u); break; } } } } while (0)
; __device__ __forceinline__ void xcd_barrier(const XcdBarrier& b) {
;     ...
;             XB_SPIN(xb_ld(&bar[XB_XGEN(b.x)]) == gen, bar);
.LBB0_339:
	global_load_dword v241, v1, s[26:27] sc1
	s_add_i32 s3, s3, 1
	s_mov_b64 s[68:69], -1
	s_waitcnt vmcnt(2)
	v_cmp_ne_u32_e32 vcc, v241, v2
	s_orn2_b64 s[34:35], vcc, exec
	s_branch .LBB0_334

; __device__ __forceinline__ unsigned xb_ld(unsigned* p)              { return __hip_atomic_load(p, __ATOMIC_RELAXED, __HIP_MEMORY_SCOPE_AGENT); }
; __device__ __forceinline__ unsigned xb_add(unsigned* p, unsigned v) { return __hip_atomic_fetch_add(p, v, __ATOMIC_RELAXED, __HIP_MEMORY_SCOPE_AGENT); }
; #define XB_SPIN(cond, bar) do { unsigned _sp = 0; while (cond) { __builtin_amdgcn_s_sleep(1); \
;     if ((++_sp & 255u) == 0u) { if (xb_ld(&(bar)[XB_TMO])) break; if (_sp > XB_SPIN_CAP) { atomicAdd(&(bar)[XB_TMO], 1u); break; } } } } while (0)
; __device__ __forceinline__ void xcd_barrier(const XcdBarrier& b) {
;     ...
;             const unsigned og = xb_add(&bar[XB_TOP], 1u);
;             const unsigned tg = og / nx;
;             if (og + 1u == (tg + 1u) * nx) xb_add(&bar[XB_TOPGEN], 1u);
;             else XB_SPIN(xb_ld(&bar[XB_TOPGEN]) == tg, bar);
.LBB0_348:
	s_or_b64 exec, exec, s[12:13]
	v_cvt_f32_u32_e32 v4, v1
	s_waitcnt vmcnt(0)
	v_readfirstlane_b32 s0, v3
	s_add_u32 s12, s78, 0x7500
	s_addc_u32 s13, s79, 0
	v_rcp_iflag_f32_e32 v4, v4
	v_add_u32_e32 v2, s0, v2
	v_add_u32_e32 v5, 1, v2
	s_mov_b64 s[20:21], -1
	v_mul_f32_e32 v3, 0x4f7ffffe, v4
	v_cvt_u32_f32_e32 v3, v3
	v_sub_u32_e32 v4, 0, v1
	v_mul_lo_u32 v4, v4, v3
	v_mul_hi_u32 v4, v3, v4
	v_add_u32_e32 v3, v3, v4
	v_mul_hi_u32 v3, v2, v3
	v_mul_lo_u32 v4, v3, v1
	v_sub_u32_e32 v2, v2, v4
	v_add_u32_e32 v6, 1, v3
	v_cmp_ge_u32_e32 vcc, v2, v1
	v_sub_u32_e32 v4, v2, v1
	s_nop 0
	v_cndmask_b32_e32 v3, v3, v6, vcc
	v_cndmask_b32_e32 v2, v2, v4, vcc
	v_add_u32_e32 v4, 1, v3
	v_cmp_ge_u32_e32 vcc, v2, v1
	s_nop 1
	v_cndmask_b32_e32 v4, v3, v4, vcc
	v_mul_lo_u32 v2, v1, v4
	v_add_u32_e32 v1, v2, v1
	v_cmp_ne_u32_e32 vcc, v5, v1
	v_mov_b64_e32 v[2:3], s[12:13]
	s_and_saveexec_b64 s[0:1], vcc
	s_cbranch_execz .LBB0_360
	v_mov_b32_e32 v1, 0
	global_load_dword v2, v1, s[12:13] sc1
	s_mov_b64 s[28:29], 0
	s_waitcnt vmcnt(0)
	v_cmp_eq_u32_e32 vcc, v2, v4
	s_and_saveexec_b64 s[26:27], vcc
	s_cbranch_execz .LBB0_359
	s_add_u32 s20, s78, 0x4200
	s_addc_u32 s21, s79, 0
	s_mov_b32 s3, 1
	global_load_dword v242, v1, s[12:13] sc1
	global_load_dword v242, v1, s[12:13] sc1
	s_branch .LBB0_352

; __device__ __forceinline__ unsigned xb_ld(unsigned* p)              { return __hip_atomic_load(p, __ATOMIC_RELAXED, __HIP_MEMORY_SCOPE_AGENT); }
; __device__ __forceinline__ unsigned xb_add(unsigned* p, unsigned v) { return __hip_atomic_fetch_add(p, v, __ATOMIC_RELAXED, __HIP_MEMORY_SCOPE_AGENT); }
; #define XB_SPIN(cond, bar) do { unsigned _sp = 0; while (cond) { __builtin_amdgcn_s_sleep(1); \
;     if ((++_sp & 255u) == 0u) { if (xb_ld(&(bar)[XB_TMO])) break; if (_sp > XB_SPIN_CAP) { atomicAdd(&(bar)[XB_TMO], 1u); break; } } } } while (0)
; __device__ __forceinline__ void xcd_barrier(const XcdBarrier& b) {
;     ...
;         unsigned nloc = b.st[0], nx = b.st[1];
;         if (nloc == 0u) { xcd_barrier_complete(bar, b.x, nloc, nx); b.st[0] = nloc; b.st[1] = nx; }
;         const unsigned old = xb_add(&bar[XB_XSUB(b.x)], 1u);
;         const unsigned gen = old / nloc;
;         if (old + 1u == (gen + 1u) * nloc) {
;             __builtin_amdgcn_fence(__ATOMIC_RELEASE, "agent");
;             asm volatile("s_waitcnt vmcnt(0)" ::: "memory");
;             const unsigned og = xb_add(&bar[XB_TOP], 1u);
;             const unsigned tg = og / nx;
;             if (og + 1u == (tg + 1u) * nx) xb_add(&bar[XB_TOPGEN], 1u);
;             else XB_SPIN(xb_ld(&bar[XB_TOPGEN]) == tg, bar);
;             __builtin_amdgcn_fence(__ATOMIC_ACQUIRE, "agent");
;             xb_add(&bar[XB_XGEN(b.x)], 1u);
;             asm volatile("s_waitcnt vmcnt(0)" ::: "memory");
;         } else {
;             XB_SPIN(xb_ld(&bar[XB_XGEN(b.x)]) == gen, bar);
.LBB0_524:
	s_or_b64 exec, exec, s[8:9]
	v_cvt_f32_u32_e32 v5, v3
	s_waitcnt vmcnt(0)
	v_readfirstlane_b32 s0, v4
	v_sub_u32_e32 v4, 0, v3
	v_rcp_iflag_f32_e32 v5, v5
	v_add_u32_e32 v6, s0, v2
	v_mul_f32_e32 v5, 0x4f7ffffe, v5
	v_cvt_u32_f32_e32 v5, v5
	v_mul_lo_u32 v2, v4, v5
	v_mul_hi_u32 v2, v5, v2
	v_add_u32_e32 v2, v5, v2
	v_mul_hi_u32 v2, v6, v2
	v_mul_lo_u32 v4, v2, v3
	v_sub_u32_e32 v4, v6, v4
	v_add_u32_e32 v5, 1, v2
	v_cmp_ge_u32_e32 vcc, v4, v3
	s_nop 1
	v_cndmask_b32_e32 v2, v2, v5, vcc
	v_sub_u32_e32 v5, v4, v3
	v_cndmask_b32_e32 v4, v4, v5, vcc
	v_add_u32_e32 v5, 1, v2
	v_cmp_ge_u32_e32 vcc, v4, v3
	v_add_u32_e32 v4, 1, v6
	s_nop 0
	v_cndmask_b32_e32 v2, v2, v5, vcc
	v_mul_lo_u32 v5, v3, v2
	v_add_u32_e32 v3, v5, v3
	v_cmp_ne_u32_e32 vcc, v4, v3
	s_and_saveexec_b64 s[0:1], vcc
	s_xor_b64 s[8:9], exec, s[0:1]
	s_cbranch_execz .LBB0_538
	s_waitcnt lgkmcnt(0)
	buffer_inv sc1
	v_mov_b32_e32 v1, 0x2000
	global_load_dword v1, v1, s[6:7] offset:1024 sc1
	s_add_u32 s28, s6, 0x2400
	s_addc_u32 s29, s7, 0
	s_waitcnt vmcnt(0)
	v_cmp_eq_u32_e32 vcc, v1, v2
	s_and_saveexec_b64 s[0:1], vcc
	s_cbranch_execz .LBB0_537
	s_add_u32 s12, s78, 0x4200
	s_addc_u32 s13, s79, 0
	s_mov_b32 s3, 1
	s_mov_b64 s[30:31], 0
	v_mov_b32_e32 v1, 0
	global_load_dword v241, v1, s[28:29] sc1
	global_load_dword v241, v1, s[28:29] sc1
	s_branch .LBB0_528

; __device__ __forceinline__ unsigned xb_ld(unsigned* p)              { return __hip_atomic_load(p, __ATOMIC_RELAXED, __HIP_MEMORY_SCOPE_AGENT); }
; #define XB_SPIN(cond, bar) do { unsigned _sp = 0; while (cond) { __builtin_amdgcn_s_sleep(1); \
;     if ((++_sp & 255u) == 0u) { if (xb_ld(&(bar)[XB_TMO])) break; if (_sp > XB_SPIN_CAP) { atomicAdd(&(bar)[XB_TMO], 1u); break; } } } } while (0)
; __device__ __forceinline__ void xcd_barrier(const XcdBarrier& b) {
;     ...
;             XB_SPIN(xb_ld(&bar[XB_XGEN(b.x)]) == gen, bar);
.LBB0_532:
	global_load_dword v241, v1, s[28:29] sc1
	s_add_i32 s3, s3, 1
	s_mov_b64 s[40:41], -1
	s_waitcnt vmcnt(2)
	v_cmp_ne_u32_e32 vcc, v241, v2
	s_orn2_b64 s[34:35], vcc, exec
	s_branch .LBB0_527

; __device__ __forceinline__ unsigned xb_ld(unsigned* p)              { return __hip_atomic_load(p, __ATOMIC_RELAXED, __HIP_MEMORY_SCOPE_AGENT); }
; __device__ __forceinline__ unsigned xb_add(unsigned* p, unsigned v) { return __hip_atomic_fetch_add(p, v, __ATOMIC_RELAXED, __HIP_MEMORY_SCOPE_AGENT); }
; #define XB_SPIN(cond, bar) do { unsigned _sp = 0; while (cond) { __builtin_amdgcn_s_sleep(1); \
;     if ((++_sp & 255u) == 0u) { if (xb_ld(&(bar)[XB_TMO])) break; if (_sp > XB_SPIN_CAP) { atomicAdd(&(bar)[XB_TMO], 1u); break; } } } } while (0)
; __device__ __forceinline__ void xcd_barrier(const XcdBarrier& b) {
;     ...
;             const unsigned og = xb_add(&bar[XB_TOP], 1u);
;             const unsigned tg = og / nx;
;             if (og + 1u == (tg + 1u) * nx) xb_add(&bar[XB_TOPGEN], 1u);
;             else XB_SPIN(xb_ld(&bar[XB_TOPGEN]) == tg, bar);
.LBB0_541:
	s_or_b64 exec, exec, s[8:9]
	v_cvt_f32_u32_e32 v4, v1
	s_waitcnt vmcnt(0)
	v_readfirstlane_b32 s0, v3
	s_add_u32 s8, s78, 0x7500
	s_addc_u32 s9, s79, 0
	v_rcp_iflag_f32_e32 v4, v4
	v_add_u32_e32 v2, s0, v2
	v_add_u32_e32 v5, 1, v2
	s_mov_b64 s[12:13], -1
	v_mul_f32_e32 v3, 0x4f7ffffe, v4
	v_cvt_u32_f32_e32 v3, v3
	v_sub_u32_e32 v4, 0, v1
	v_mul_lo_u32 v4, v4, v3
	v_mul_hi_u32 v4, v3, v4
	v_add_u32_e32 v3, v3, v4
	v_mul_hi_u32 v3, v2, v3
	v_mul_lo_u32 v4, v3, v1
	v_sub_u32_e32 v2, v2, v4
	v_add_u32_e32 v6, 1, v3
	v_cmp_ge_u32_e32 vcc, v2, v1
	v_sub_u32_e32 v4, v2, v1
	s_nop 0
	v_cndmask_b32_e32 v3, v3, v6, vcc
	v_cndmask_b32_e32 v2, v2, v4, vcc
	v_add_u32_e32 v4, 1, v3
	v_cmp_ge_u32_e32 vcc, v2, v1
	s_nop 1
	v_cndmask_b32_e32 v4, v3, v4, vcc
	v_mul_lo_u32 v2, v1, v4
	v_add_u32_e32 v1, v2, v1
	v_cmp_ne_u32_e32 vcc, v5, v1
	v_mov_b64_e32 v[2:3], s[8:9]
	s_and_saveexec_b64 s[0:1], vcc
	s_cbranch_execz .LBB0_553
	v_mov_b32_e32 v1, 0
	global_load_dword v2, v1, s[8:9] sc1
	s_mov_b64 s[30:31], 0
	s_waitcnt vmcnt(0)
	v_cmp_eq_u32_e32 vcc, v2, v4
	s_and_saveexec_b64 s[28:29], vcc
	s_cbranch_execz .LBB0_552
	s_add_u32 s12, s78, 0x4200
	s_addc_u32 s13, s79, 0
	s_mov_b32 s3, 1
	global_load_dword v242, v1, s[8:9] sc1
	global_load_dword v242, v1, s[8:9] sc1
	s_branch .LBB0_545

; __device__ __forceinline__ unsigned xb_ld(unsigned* p)              { return __hip_atomic_load(p, __ATOMIC_RELAXED, __HIP_MEMORY_SCOPE_AGENT); }
; #define XB_SPIN(cond, bar) do { unsigned _sp = 0; while (cond) { __builtin_amdgcn_s_sleep(1); \
;     if ((++_sp & 255u) == 0u) { if (xb_ld(&(bar)[XB_TMO])) break; if (_sp > XB_SPIN_CAP) { atomicAdd(&(bar)[XB_TMO], 1u); break; } } } } while (0)
; __device__ __forceinline__ void xcd_barrier(const XcdBarrier& b) {
;     ...
;             else XB_SPIN(xb_ld(&bar[XB_TOPGEN]) == tg, bar);
.LBB0_549:
	global_load_dword v242, v1, s[8:9] sc1
	s_add_i32 s3, s3, 1
	s_mov_b64 s[34:35], -1
	s_waitcnt vmcnt(2)
	v_cmp_ne_u32_e32 vcc, v242, v4
	s_orn2_b64 s[42:43], vcc, exec
	s_branch .LBB0_544

; __device__ __forceinline__ unsigned xb_ld(unsigned* p)              { return __hip_atomic_load(p, __ATOMIC_RELAXED, __HIP_MEMORY_SCOPE_AGENT); }
; __device__ __forceinline__ unsigned xb_add(unsigned* p, unsigned v) { return __hip_atomic_fetch_add(p, v, __ATOMIC_RELAXED, __HIP_MEMORY_SCOPE_AGENT); }
; #define XB_SPIN(cond, bar) do { unsigned _sp = 0; while (cond) { __builtin_amdgcn_s_sleep(1); \
;     if ((++_sp & 255u) == 0u) { if (xb_ld(&(bar)[XB_TMO])) break; if (_sp > XB_SPIN_CAP) { atomicAdd(&(bar)[XB_TMO], 1u); break; } } } } while (0)
; __device__ __forceinline__ void xcd_barrier(const XcdBarrier& b) {
;     ...
;         unsigned nloc = b.st[0], nx = b.st[1];
;         if (nloc == 0u) { xcd_barrier_complete(bar, b.x, nloc, nx); b.st[0] = nloc; b.st[1] = nx; }
;         const unsigned old = xb_add(&bar[XB_XSUB(b.x)], 1u);
;         const unsigned gen = old / nloc;
;         if (old + 1u == (gen + 1u) * nloc) {
;             __builtin_amdgcn_fence(__ATOMIC_RELEASE, "agent");
;             asm volatile("s_waitcnt vmcnt(0)" ::: "memory");
;             const unsigned og = xb_add(&bar[XB_TOP], 1u);
;             const unsigned tg = og / nx;
;             if (og + 1u == (tg + 1u) * nx) xb_add(&bar[XB_TOPGEN], 1u);
;             else XB_SPIN(xb_ld(&bar[XB_TOPGEN]) == tg, bar);
;             __builtin_amdgcn_fence(__ATOMIC_ACQUIRE, "agent");
;             xb_add(&bar[XB_XGEN(b.x)], 1u);
;             asm volatile("s_waitcnt vmcnt(0)" ::: "memory");
;         } else {
;             XB_SPIN(xb_ld(&bar[XB_XGEN(b.x)]) == gen, bar);
.LBB0_641:
	s_or_b64 exec, exec, s[8:9]
	v_cvt_f32_u32_e32 v5, v3
	s_waitcnt vmcnt(0)
	v_readfirstlane_b32 s0, v4
	v_sub_u32_e32 v4, 0, v3
	v_rcp_iflag_f32_e32 v5, v5
	v_add_u32_e32 v6, s0, v2
	v_mul_f32_e32 v5, 0x4f7ffffe, v5
	v_cvt_u32_f32_e32 v5, v5
	v_mul_lo_u32 v2, v4, v5
	v_mul_hi_u32 v2, v5, v2
	v_add_u32_e32 v2, v5, v2
	v_mul_hi_u32 v2, v6, v2
	v_mul_lo_u32 v4, v2, v3
	v_sub_u32_e32 v4, v6, v4
	v_add_u32_e32 v5, 1, v2
	v_cmp_ge_u32_e32 vcc, v4, v3
	s_nop 1
	v_cndmask_b32_e32 v2, v2, v5, vcc
	v_sub_u32_e32 v5, v4, v3
	v_cndmask_b32_e32 v4, v4, v5, vcc
	v_add_u32_e32 v5, 1, v2
	v_cmp_ge_u32_e32 vcc, v4, v3
	v_add_u32_e32 v4, 1, v6
	s_nop 0
	v_cndmask_b32_e32 v2, v2, v5, vcc
	v_mul_lo_u32 v5, v3, v2
	v_add_u32_e32 v3, v5, v3
	v_cmp_ne_u32_e32 vcc, v4, v3
	s_and_saveexec_b64 s[0:1], vcc
	s_xor_b64 s[8:9], exec, s[0:1]
	s_cbranch_execz .LBB0_655
	s_waitcnt lgkmcnt(0)
	buffer_inv sc1
	v_mov_b32_e32 v1, 0x2000
	global_load_dword v1, v1, s[6:7] offset:1024 sc1
	s_add_u32 s42, s6, 0x2400
	s_addc_u32 s43, s7, 0
	s_waitcnt vmcnt(0)
	v_cmp_eq_u32_e32 vcc, v1, v2
	s_and_saveexec_b64 s[0:1], vcc
	s_cbranch_execz .LBB0_654
	s_add_u32 s12, s78, 0x4200
	s_addc_u32 s13, s79, 0
	s_mov_b32 s3, 1
	s_mov_b64 s[44:45], 0
	v_mov_b32_e32 v1, 0
	global_load_dword v241, v1, s[42:43] sc1
	global_load_dword v241, v1, s[42:43] sc1
	s_branch .LBB0_645

; __device__ __forceinline__ unsigned xb_ld(unsigned* p)              { return __hip_atomic_load(p, __ATOMIC_RELAXED, __HIP_MEMORY_SCOPE_AGENT); }
; #define XB_SPIN(cond, bar) do { unsigned _sp = 0; while (cond) { __builtin_amdgcn_s_sleep(1); \
;     if ((++_sp & 255u) == 0u) { if (xb_ld(&(bar)[XB_TMO])) break; if (_sp > XB_SPIN_CAP) { atomicAdd(&(bar)[XB_TMO], 1u); break; } } } } while (0)
; __device__ __forceinline__ void xcd_barrier(const XcdBarrier& b) {
;     ...
;             XB_SPIN(xb_ld(&bar[XB_XGEN(b.x)]) == gen, bar);
.LBB0_649:
	global_load_dword v241, v1, s[42:43] sc1
	s_add_i32 s3, s3, 1
	s_mov_b64 s[52:53], -1
	s_waitcnt vmcnt(2)
	v_cmp_ne_u32_e32 vcc, v241, v2
	s_orn2_b64 s[34:35], vcc, exec
	s_branch .LBB0_644

; __device__ __forceinline__ unsigned xb_ld(unsigned* p)              { return __hip_atomic_load(p, __ATOMIC_RELAXED, __HIP_MEMORY_SCOPE_AGENT); }
; __device__ __forceinline__ unsigned xb_add(unsigned* p, unsigned v) { return __hip_atomic_fetch_add(p, v, __ATOMIC_RELAXED, __HIP_MEMORY_SCOPE_AGENT); }
; #define XB_SPIN(cond, bar) do { unsigned _sp = 0; while (cond) { __builtin_amdgcn_s_sleep(1); \
;     if ((++_sp & 255u) == 0u) { if (xb_ld(&(bar)[XB_TMO])) break; if (_sp > XB_SPIN_CAP) { atomicAdd(&(bar)[XB_TMO], 1u); break; } } } } while (0)
; __device__ __forceinline__ void xcd_barrier(const XcdBarrier& b) {
;     ...
;             const unsigned og = xb_add(&bar[XB_TOP], 1u);
;             const unsigned tg = og / nx;
;             if (og + 1u == (tg + 1u) * nx) xb_add(&bar[XB_TOPGEN], 1u);
;             else XB_SPIN(xb_ld(&bar[XB_TOPGEN]) == tg, bar);
.LBB0_658:
	s_or_b64 exec, exec, s[8:9]
	v_cvt_f32_u32_e32 v4, v1
	s_waitcnt vmcnt(0)
	v_readfirstlane_b32 s0, v3
	s_add_u32 s8, s78, 0x7500
	s_addc_u32 s9, s79, 0
	v_rcp_iflag_f32_e32 v4, v4
	v_add_u32_e32 v2, s0, v2
	v_add_u32_e32 v5, 1, v2
	s_mov_b64 s[12:13], -1
	v_mul_f32_e32 v3, 0x4f7ffffe, v4
	v_cvt_u32_f32_e32 v3, v3
	v_sub_u32_e32 v4, 0, v1
	v_mul_lo_u32 v4, v4, v3
	v_mul_hi_u32 v4, v3, v4
	v_add_u32_e32 v3, v3, v4
	v_mul_hi_u32 v3, v2, v3
	v_mul_lo_u32 v4, v3, v1
	v_sub_u32_e32 v2, v2, v4
	v_add_u32_e32 v6, 1, v3
	v_cmp_ge_u32_e32 vcc, v2, v1
	v_sub_u32_e32 v4, v2, v1
	s_nop 0
	v_cndmask_b32_e32 v3, v3, v6, vcc
	v_cndmask_b32_e32 v2, v2, v4, vcc
	v_add_u32_e32 v4, 1, v3
	v_cmp_ge_u32_e32 vcc, v2, v1
	s_nop 1
	v_cndmask_b32_e32 v4, v3, v4, vcc
	v_mul_lo_u32 v2, v1, v4
	v_add_u32_e32 v1, v2, v1
	v_cmp_ne_u32_e32 vcc, v5, v1
	v_mov_b64_e32 v[2:3], s[8:9]
	s_and_saveexec_b64 s[0:1], vcc
	s_cbranch_execz .LBB0_670
	v_mov_b32_e32 v1, 0
	global_load_dword v2, v1, s[8:9] sc1
	s_mov_b64 s[34:35], 0
	s_waitcnt vmcnt(0)
	v_cmp_eq_u32_e32 vcc, v2, v4
	s_and_saveexec_b64 s[42:43], vcc
	s_cbranch_execz .LBB0_669
	s_add_u32 s12, s78, 0x4200
	s_addc_u32 s13, s79, 0
	s_mov_b32 s3, 1
	s_mov_b64 s[44:45], 0
	global_load_dword v242, v1, s[8:9] sc1
	global_load_dword v242, v1, s[8:9] sc1
	s_branch .LBB0_662

; __device__ __forceinline__ unsigned xb_ld(unsigned* p)              { return __hip_atomic_load(p, __ATOMIC_RELAXED, __HIP_MEMORY_SCOPE_AGENT); }
; #define XB_SPIN(cond, bar) do { unsigned _sp = 0; while (cond) { __builtin_amdgcn_s_sleep(1); \
;     if ((++_sp & 255u) == 0u) { if (xb_ld(&(bar)[XB_TMO])) break; if (_sp > XB_SPIN_CAP) { atomicAdd(&(bar)[XB_TMO], 1u); break; } } } } while (0)
; __device__ __forceinline__ void xcd_barrier(const XcdBarrier& b) {
;     ...
;             else XB_SPIN(xb_ld(&bar[XB_TOPGEN]) == tg, bar);
.LBB0_666:
	global_load_dword v242, v1, s[8:9] sc1
	s_add_i32 s3, s3, 1
	s_mov_b64 s[34:35], -1
	s_waitcnt vmcnt(2)
	v_cmp_ne_u32_e32 vcc, v242, v4
	s_orn2_b64 s[54:55], vcc, exec
	s_branch .LBB0_661

; __device__ __forceinline__ unsigned xb_ld(unsigned* p)              { return __hip_atomic_load(p, __ATOMIC_RELAXED, __HIP_MEMORY_SCOPE_AGENT); }
; __device__ __forceinline__ unsigned xb_add(unsigned* p, unsigned v) { return __hip_atomic_fetch_add(p, v, __ATOMIC_RELAXED, __HIP_MEMORY_SCOPE_AGENT); }
; #define XB_SPIN(cond, bar) do { unsigned _sp = 0; while (cond) { __builtin_amdgcn_s_sleep(1); \
;     if ((++_sp & 255u) == 0u) { if (xb_ld(&(bar)[XB_TMO])) break; if (_sp > XB_SPIN_CAP) { atomicAdd(&(bar)[XB_TMO], 1u); break; } } } } while (0)
; __device__ __forceinline__ void xcd_barrier(const XcdBarrier& b) {
;     ...
;         unsigned nloc = b.st[0], nx = b.st[1];
;         if (nloc == 0u) { xcd_barrier_complete(bar, b.x, nloc, nx); b.st[0] = nloc; b.st[1] = nx; }
;         const unsigned old = xb_add(&bar[XB_XSUB(b.x)], 1u);
;         const unsigned gen = old / nloc;
;         if (old + 1u == (gen + 1u) * nloc) {
;             __builtin_amdgcn_fence(__ATOMIC_RELEASE, "agent");
;             asm volatile("s_waitcnt vmcnt(0)" ::: "memory");
;             const unsigned og = xb_add(&bar[XB_TOP], 1u);
;             const unsigned tg = og / nx;
;             if (og + 1u == (tg + 1u) * nx) xb_add(&bar[XB_TOPGEN], 1u);
;             else XB_SPIN(xb_ld(&bar[XB_TOPGEN]) == tg, bar);
;             __builtin_amdgcn_fence(__ATOMIC_ACQUIRE, "agent");
;             xb_add(&bar[XB_XGEN(b.x)], 1u);
;             asm volatile("s_waitcnt vmcnt(0)" ::: "memory");
;         } else {
;             XB_SPIN(xb_ld(&bar[XB_XGEN(b.x)]) == gen, bar);
.LBB0_723:
	s_or_b64 exec, exec, s[8:9]
	v_cvt_f32_u32_e32 v5, v3
	s_waitcnt vmcnt(0)
	v_readfirstlane_b32 s0, v4
	v_sub_u32_e32 v4, 0, v3
	v_rcp_iflag_f32_e32 v5, v5
	v_add_u32_e32 v6, s0, v2
	v_mul_f32_e32 v5, 0x4f7ffffe, v5
	v_cvt_u32_f32_e32 v5, v5
	v_mul_lo_u32 v2, v4, v5
	v_mul_hi_u32 v2, v5, v2
	v_add_u32_e32 v2, v5, v2
	v_mul_hi_u32 v2, v6, v2
	v_mul_lo_u32 v4, v2, v3
	v_sub_u32_e32 v4, v6, v4
	v_add_u32_e32 v5, 1, v2
	v_cmp_ge_u32_e32 vcc, v4, v3
	s_nop 1
	v_cndmask_b32_e32 v2, v2, v5, vcc
	v_sub_u32_e32 v5, v4, v3
	v_cndmask_b32_e32 v4, v4, v5, vcc
	v_add_u32_e32 v5, 1, v2
	v_cmp_ge_u32_e32 vcc, v4, v3
	v_add_u32_e32 v4, 1, v6
	s_nop 0
	v_cndmask_b32_e32 v2, v2, v5, vcc
	v_mul_lo_u32 v5, v3, v2
	v_add_u32_e32 v3, v5, v3
	v_cmp_ne_u32_e32 vcc, v4, v3
	s_and_saveexec_b64 s[0:1], vcc
	s_xor_b64 s[8:9], exec, s[0:1]
	s_cbranch_execz .LBB0_737
	s_waitcnt lgkmcnt(0)
	buffer_inv sc1
	v_mov_b32_e32 v1, 0x2000
	global_load_dword v1, v1, s[6:7] offset:1024 sc1
	s_add_u32 s36, s6, 0x2400
	s_addc_u32 s37, s7, 0
	s_waitcnt vmcnt(0)
	v_cmp_eq_u32_e32 vcc, v1, v2
	s_and_saveexec_b64 s[0:1], vcc
	s_cbranch_execz .LBB0_736
	s_add_u32 s12, s78, 0x4200
	s_addc_u32 s13, s79, 0
	s_mov_b32 s3, 1
	s_mov_b64 s[40:41], 0
	v_mov_b32_e32 v1, 0
	global_load_dword v241, v1, s[36:37] sc1
	global_load_dword v241, v1, s[36:37] sc1
	s_branch .LBB0_727

; __device__ __forceinline__ unsigned xb_ld(unsigned* p)              { return __hip_atomic_load(p, __ATOMIC_RELAXED, __HIP_MEMORY_SCOPE_AGENT); }
; #define XB_SPIN(cond, bar) do { unsigned _sp = 0; while (cond) { __builtin_amdgcn_s_sleep(1); \
;     if ((++_sp & 255u) == 0u) { if (xb_ld(&(bar)[XB_TMO])) break; if (_sp > XB_SPIN_CAP) { atomicAdd(&(bar)[XB_TMO], 1u); break; } } } } while (0)
; __device__ __forceinline__ void xcd_barrier(const XcdBarrier& b) {
;     ...
;             XB_SPIN(xb_ld(&bar[XB_XGEN(b.x)]) == gen, bar);
.LBB0_731:
	global_load_dword v241, v1, s[36:37] sc1
	s_add_i32 s3, s3, 1
	s_mov_b64 s[44:45], -1
	s_waitcnt vmcnt(2)
	v_cmp_ne_u32_e32 vcc, v241, v2
	s_orn2_b64 s[34:35], vcc, exec
	s_branch .LBB0_726

; __device__ __forceinline__ unsigned xb_ld(unsigned* p)              { return __hip_atomic_load(p, __ATOMIC_RELAXED, __HIP_MEMORY_SCOPE_AGENT); }
; __device__ __forceinline__ unsigned xb_add(unsigned* p, unsigned v) { return __hip_atomic_fetch_add(p, v, __ATOMIC_RELAXED, __HIP_MEMORY_SCOPE_AGENT); }
; #define XB_SPIN(cond, bar) do { unsigned _sp = 0; while (cond) { __builtin_amdgcn_s_sleep(1); \
;     if ((++_sp & 255u) == 0u) { if (xb_ld(&(bar)[XB_TMO])) break; if (_sp > XB_SPIN_CAP) { atomicAdd(&(bar)[XB_TMO], 1u); break; } } } } while (0)
; __device__ __forceinline__ void xcd_barrier(const XcdBarrier& b) {
;     ...
;             const unsigned og = xb_add(&bar[XB_TOP], 1u);
;             const unsigned tg = og / nx;
;             if (og + 1u == (tg + 1u) * nx) xb_add(&bar[XB_TOPGEN], 1u);
;             else XB_SPIN(xb_ld(&bar[XB_TOPGEN]) == tg, bar);
.LBB0_740:
	s_or_b64 exec, exec, s[8:9]
	v_cvt_f32_u32_e32 v4, v1
	s_waitcnt vmcnt(0)
	v_readfirstlane_b32 s0, v3
	s_add_u32 s8, s78, 0x7500
	s_addc_u32 s9, s79, 0
	v_rcp_iflag_f32_e32 v4, v4
	v_add_u32_e32 v2, s0, v2
	v_add_u32_e32 v5, 1, v2
	s_mov_b64 s[12:13], -1
	v_mul_f32_e32 v3, 0x4f7ffffe, v4
	v_cvt_u32_f32_e32 v3, v3
	v_sub_u32_e32 v4, 0, v1
	v_mul_lo_u32 v4, v4, v3
	v_mul_hi_u32 v4, v3, v4
	v_add_u32_e32 v3, v3, v4
	v_mul_hi_u32 v3, v2, v3
	v_mul_lo_u32 v4, v3, v1
	v_sub_u32_e32 v2, v2, v4
	v_add_u32_e32 v6, 1, v3
	v_cmp_ge_u32_e32 vcc, v2, v1
	v_sub_u32_e32 v4, v2, v1
	s_nop 0
	v_cndmask_b32_e32 v3, v3, v6, vcc
	v_cndmask_b32_e32 v2, v2, v4, vcc
	v_add_u32_e32 v4, 1, v3
	v_cmp_ge_u32_e32 vcc, v2, v1
	s_nop 1
	v_cndmask_b32_e32 v4, v3, v4, vcc
	v_mul_lo_u32 v2, v1, v4
	v_add_u32_e32 v1, v2, v1
	v_cmp_ne_u32_e32 vcc, v5, v1
	v_mov_b64_e32 v[2:3], s[8:9]
	s_and_saveexec_b64 s[0:1], vcc
	s_cbranch_execz .LBB0_752
	v_mov_b32_e32 v1, 0
	global_load_dword v2, v1, s[8:9] sc1
	s_mov_b64 s[34:35], 0
	s_waitcnt vmcnt(0)
	v_cmp_eq_u32_e32 vcc, v2, v4
	s_and_saveexec_b64 s[36:37], vcc
	s_cbranch_execz .LBB0_751
	s_add_u32 s12, s78, 0x4200
	s_addc_u32 s13, s79, 0
	s_mov_b32 s3, 1
	s_mov_b64 s[40:41], 0
	global_load_dword v242, v1, s[8:9] sc1
	global_load_dword v242, v1, s[8:9] sc1
	s_branch .LBB0_744

; __device__ __forceinline__ unsigned xb_ld(unsigned* p)              { return __hip_atomic_load(p, __ATOMIC_RELAXED, __HIP_MEMORY_SCOPE_AGENT); }
; #define XB_SPIN(cond, bar) do { unsigned _sp = 0; while (cond) { __builtin_amdgcn_s_sleep(1); \
;     if ((++_sp & 255u) == 0u) { if (xb_ld(&(bar)[XB_TMO])) break; if (_sp > XB_SPIN_CAP) { atomicAdd(&(bar)[XB_TMO], 1u); break; } } } } while (0)
; __device__ __forceinline__ void xcd_barrier(const XcdBarrier& b) {
;     ...
;             else XB_SPIN(xb_ld(&bar[XB_TOPGEN]) == tg, bar);
.LBB0_748:
	global_load_dword v242, v1, s[8:9] sc1
	s_add_i32 s3, s3, 1
	s_mov_b64 s[34:35], -1
	s_waitcnt vmcnt(2)
	v_cmp_ne_u32_e32 vcc, v242, v4
	s_orn2_b64 s[46:47], vcc, exec
	s_branch .LBB0_743

; __device__ __forceinline__ unsigned xb_ld(unsigned* p)              { return __hip_atomic_load(p, __ATOMIC_RELAXED, __HIP_MEMORY_SCOPE_AGENT); }
; __device__ __forceinline__ unsigned xb_add(unsigned* p, unsigned v) { return __hip_atomic_fetch_add(p, v, __ATOMIC_RELAXED, __HIP_MEMORY_SCOPE_AGENT); }
; #define XB_SPIN(cond, bar) do { unsigned _sp = 0; while (cond) { __builtin_amdgcn_s_sleep(1); \
;     if ((++_sp & 255u) == 0u) { if (xb_ld(&(bar)[XB_TMO])) break; if (_sp > XB_SPIN_CAP) { atomicAdd(&(bar)[XB_TMO], 1u); break; } } } } while (0)
; __device__ __forceinline__ void xcd_barrier(const XcdBarrier& b) {
;     ...
;         unsigned nloc = b.st[0], nx = b.st[1];
;         if (nloc == 0u) { xcd_barrier_complete(bar, b.x, nloc, nx); b.st[0] = nloc; b.st[1] = nx; }
;         const unsigned old = xb_add(&bar[XB_XSUB(b.x)], 1u);
;         const unsigned gen = old / nloc;
;         if (old + 1u == (gen + 1u) * nloc) {
;             __builtin_amdgcn_fence(__ATOMIC_RELEASE, "agent");
;             asm volatile("s_waitcnt vmcnt(0)" ::: "memory");
;             const unsigned og = xb_add(&bar[XB_TOP], 1u);
;             const unsigned tg = og / nx;
;             if (og + 1u == (tg + 1u) * nx) xb_add(&bar[XB_TOPGEN], 1u);
;             else XB_SPIN(xb_ld(&bar[XB_TOPGEN]) == tg, bar);
;             __builtin_amdgcn_fence(__ATOMIC_ACQUIRE, "agent");
;             xb_add(&bar[XB_XGEN(b.x)], 1u);
;             asm volatile("s_waitcnt vmcnt(0)" ::: "memory");
;         } else {
;             XB_SPIN(xb_ld(&bar[XB_XGEN(b.x)]) == gen, bar);
.LBB0_977:
	s_or_b64 exec, exec, s[8:9]
	v_cvt_f32_u32_e32 v5, v3
	s_waitcnt vmcnt(0)
	v_readfirstlane_b32 s0, v4
	v_sub_u32_e32 v4, 0, v3
	v_rcp_iflag_f32_e32 v5, v5
	v_add_u32_e32 v6, s0, v2
	v_mul_f32_e32 v5, 0x4f7ffffe, v5
	v_cvt_u32_f32_e32 v5, v5
	v_mul_lo_u32 v2, v4, v5
	v_mul_hi_u32 v2, v5, v2
	v_add_u32_e32 v2, v5, v2
	v_mul_hi_u32 v2, v6, v2
	v_mul_lo_u32 v4, v2, v3
	v_sub_u32_e32 v4, v6, v4
	v_add_u32_e32 v5, 1, v2
	v_cmp_ge_u32_e32 vcc, v4, v3
	s_nop 1
	v_cndmask_b32_e32 v2, v2, v5, vcc
	v_sub_u32_e32 v5, v4, v3
	v_cndmask_b32_e32 v4, v4, v5, vcc
	v_add_u32_e32 v5, 1, v2
	v_cmp_ge_u32_e32 vcc, v4, v3
	v_add_u32_e32 v4, 1, v6
	s_nop 0
	v_cndmask_b32_e32 v2, v2, v5, vcc
	v_mul_lo_u32 v5, v3, v2
	v_add_u32_e32 v3, v5, v3
	v_cmp_ne_u32_e32 vcc, v4, v3
	s_and_saveexec_b64 s[0:1], vcc
	s_xor_b64 s[8:9], exec, s[0:1]
	s_cbranch_execz .LBB0_991
	s_waitcnt lgkmcnt(0)
	buffer_inv sc1
	v_mov_b32_e32 v1, 0x2000
	global_load_dword v1, v1, s[6:7] offset:1024 sc1
	s_add_u32 s14, s6, 0x2400
	s_addc_u32 s15, s7, 0
	s_waitcnt vmcnt(0)
	v_cmp_eq_u32_e32 vcc, v1, v2
	s_and_saveexec_b64 s[0:1], vcc
	s_cbranch_execz .LBB0_990
	s_add_u32 s12, s78, 0x4200
	s_addc_u32 s13, s79, 0
	s_mov_b32 s3, 1
	s_mov_b64 s[22:23], 0
	v_mov_b32_e32 v1, 0
	global_load_dword v241, v1, s[14:15] sc1
	global_load_dword v241, v1, s[14:15] sc1
	s_branch .LBB0_981

; __device__ __forceinline__ unsigned xb_ld(unsigned* p)              { return __hip_atomic_load(p, __ATOMIC_RELAXED, __HIP_MEMORY_SCOPE_AGENT); }
; #define XB_SPIN(cond, bar) do { unsigned _sp = 0; while (cond) { __builtin_amdgcn_s_sleep(1); \
;     if ((++_sp & 255u) == 0u) { if (xb_ld(&(bar)[XB_TMO])) break; if (_sp > XB_SPIN_CAP) { atomicAdd(&(bar)[XB_TMO], 1u); break; } } } } while (0)
; __device__ __forceinline__ void xcd_barrier(const XcdBarrier& b) {
;     ...
;             XB_SPIN(xb_ld(&bar[XB_XGEN(b.x)]) == gen, bar);
.LBB0_985:
	global_load_dword v241, v1, s[14:15] sc1
	s_add_i32 s3, s3, 1
	s_mov_b64 s[34:35], -1
	s_waitcnt vmcnt(2)
	v_cmp_ne_u32_e32 vcc, v241, v2
	s_orn2_b64 s[30:31], vcc, exec
	s_branch .LBB0_980

; __device__ __forceinline__ unsigned xb_ld(unsigned* p)              { return __hip_atomic_load(p, __ATOMIC_RELAXED, __HIP_MEMORY_SCOPE_AGENT); }
; __device__ __forceinline__ unsigned xb_add(unsigned* p, unsigned v) { return __hip_atomic_fetch_add(p, v, __ATOMIC_RELAXED, __HIP_MEMORY_SCOPE_AGENT); }
; #define XB_SPIN(cond, bar) do { unsigned _sp = 0; while (cond) { __builtin_amdgcn_s_sleep(1); \
;     if ((++_sp & 255u) == 0u) { if (xb_ld(&(bar)[XB_TMO])) break; if (_sp > XB_SPIN_CAP) { atomicAdd(&(bar)[XB_TMO], 1u); break; } } } } while (0)
; __device__ __forceinline__ void xcd_barrier(const XcdBarrier& b) {
;     ...
;             const unsigned og = xb_add(&bar[XB_TOP], 1u);
;             const unsigned tg = og / nx;
;             if (og + 1u == (tg + 1u) * nx) xb_add(&bar[XB_TOPGEN], 1u);
;             else XB_SPIN(xb_ld(&bar[XB_TOPGEN]) == tg, bar);
.LBB0_994:
	s_or_b64 exec, exec, s[8:9]
	v_cvt_f32_u32_e32 v4, v1
	s_waitcnt vmcnt(0)
	v_readfirstlane_b32 s0, v3
	s_add_u32 s8, s78, 0x7500
	s_addc_u32 s9, s79, 0
	v_rcp_iflag_f32_e32 v4, v4
	v_add_u32_e32 v2, s0, v2
	v_add_u32_e32 v5, 1, v2
	s_mov_b64 s[12:13], -1
	v_mul_f32_e32 v3, 0x4f7ffffe, v4
	v_cvt_u32_f32_e32 v3, v3
	v_sub_u32_e32 v4, 0, v1
	v_mul_lo_u32 v4, v4, v3
	v_mul_hi_u32 v4, v3, v4
	v_add_u32_e32 v3, v3, v4
	v_mul_hi_u32 v3, v2, v3
	v_mul_lo_u32 v4, v3, v1
	v_sub_u32_e32 v2, v2, v4
	v_add_u32_e32 v6, 1, v3
	v_cmp_ge_u32_e32 vcc, v2, v1
	v_sub_u32_e32 v4, v2, v1
	s_nop 0
	v_cndmask_b32_e32 v3, v3, v6, vcc
	v_cndmask_b32_e32 v2, v2, v4, vcc
	v_add_u32_e32 v4, 1, v3
	v_cmp_ge_u32_e32 vcc, v2, v1
	s_nop 1
	v_cndmask_b32_e32 v4, v3, v4, vcc
	v_mul_lo_u32 v2, v1, v4
	v_add_u32_e32 v1, v2, v1
	v_cmp_ne_u32_e32 vcc, v5, v1
	v_mov_b64_e32 v[2:3], s[8:9]
	s_and_saveexec_b64 s[0:1], vcc
	s_cbranch_execz .LBB0_1006
	v_mov_b32_e32 v1, 0
	global_load_dword v2, v1, s[8:9] sc1
	s_mov_b64 s[22:23], 0
	s_waitcnt vmcnt(0)
	v_cmp_eq_u32_e32 vcc, v2, v4
	s_and_saveexec_b64 s[14:15], vcc
	s_cbranch_execz .LBB0_1005
	s_add_u32 s12, s78, 0x4200
	s_addc_u32 s13, s79, 0
	s_mov_b32 s3, 1
	global_load_dword v242, v1, s[8:9] sc1
	global_load_dword v242, v1, s[8:9] sc1
	s_branch .LBB0_998

; __device__ __forceinline__ unsigned xb_ld(unsigned* p)              { return __hip_atomic_load(p, __ATOMIC_RELAXED, __HIP_MEMORY_SCOPE_AGENT); }
; #define XB_SPIN(cond, bar) do { unsigned _sp = 0; while (cond) { __builtin_amdgcn_s_sleep(1); \
;     if ((++_sp & 255u) == 0u) { if (xb_ld(&(bar)[XB_TMO])) break; if (_sp > XB_SPIN_CAP) { atomicAdd(&(bar)[XB_TMO], 1u); break; } } } } while (0)
; __device__ __forceinline__ void xcd_barrier(const XcdBarrier& b) {
;     ...
;             else XB_SPIN(xb_ld(&bar[XB_TOPGEN]) == tg, bar);
.LBB0_1002:
	global_load_dword v242, v1, s[8:9] sc1
	s_add_i32 s3, s3, 1
	s_mov_b64 s[30:31], -1
	s_waitcnt vmcnt(2)
	v_cmp_ne_u32_e32 vcc, v242, v4
	s_orn2_b64 s[36:37], vcc, exec
	s_branch .LBB0_997

; __device__ __forceinline__ unsigned xb_ld(unsigned* p)              { return __hip_atomic_load(p, __ATOMIC_RELAXED, __HIP_MEMORY_SCOPE_AGENT); }
; __device__ __forceinline__ unsigned xb_add(unsigned* p, unsigned v) { return __hip_atomic_fetch_add(p, v, __ATOMIC_RELAXED, __HIP_MEMORY_SCOPE_AGENT); }
; #define XB_SPIN(cond, bar) do { unsigned _sp = 0; while (cond) { __builtin_amdgcn_s_sleep(1); \
;     if ((++_sp & 255u) == 0u) { if (xb_ld(&(bar)[XB_TMO])) break; if (_sp > XB_SPIN_CAP) { atomicAdd(&(bar)[XB_TMO], 1u); break; } } } } while (0)
; __device__ __forceinline__ void xcd_barrier(const XcdBarrier& b) {
;     ...
;         unsigned nloc = b.st[0], nx = b.st[1];
;         if (nloc == 0u) { xcd_barrier_complete(bar, b.x, nloc, nx); b.st[0] = nloc; b.st[1] = nx; }
;         const unsigned old = xb_add(&bar[XB_XSUB(b.x)], 1u);
;         const unsigned gen = old / nloc;
;         if (old + 1u == (gen + 1u) * nloc) {
;             __builtin_amdgcn_fence(__ATOMIC_RELEASE, "agent");
;             asm volatile("s_waitcnt vmcnt(0)" ::: "memory");
;             const unsigned og = xb_add(&bar[XB_TOP], 1u);
;             const unsigned tg = og / nx;
;             if (og + 1u == (tg + 1u) * nx) xb_add(&bar[XB_TOPGEN], 1u);
;             else XB_SPIN(xb_ld(&bar[XB_TOPGEN]) == tg, bar);
;             __builtin_amdgcn_fence(__ATOMIC_ACQUIRE, "agent");
;             xb_add(&bar[XB_XGEN(b.x)], 1u);
;             asm volatile("s_waitcnt vmcnt(0)" ::: "memory");
;         } else {
;             XB_SPIN(xb_ld(&bar[XB_XGEN(b.x)]) == gen, bar);
.LBB0_1132:
	s_or_b64 exec, exec, s[8:9]
	v_cvt_f32_u32_e32 v5, v3
	s_waitcnt vmcnt(0)
	v_readfirstlane_b32 s0, v4
	v_sub_u32_e32 v4, 0, v3
	v_rcp_iflag_f32_e32 v5, v5
	v_add_u32_e32 v6, s0, v2
	v_mul_f32_e32 v5, 0x4f7ffffe, v5
	v_cvt_u32_f32_e32 v5, v5
	v_mul_lo_u32 v2, v4, v5
	v_mul_hi_u32 v2, v5, v2
	v_add_u32_e32 v2, v5, v2
	v_mul_hi_u32 v2, v6, v2
	v_mul_lo_u32 v4, v2, v3
	v_sub_u32_e32 v4, v6, v4
	v_add_u32_e32 v5, 1, v2
	v_cmp_ge_u32_e32 vcc, v4, v3
	s_nop 1
	v_cndmask_b32_e32 v2, v2, v5, vcc
	v_sub_u32_e32 v5, v4, v3
	v_cndmask_b32_e32 v4, v4, v5, vcc
	v_add_u32_e32 v5, 1, v2
	v_cmp_ge_u32_e32 vcc, v4, v3
	v_add_u32_e32 v4, 1, v6
	s_nop 0
	v_cndmask_b32_e32 v2, v2, v5, vcc
	v_mul_lo_u32 v5, v3, v2
	v_add_u32_e32 v3, v5, v3
	v_cmp_ne_u32_e32 vcc, v4, v3
	s_and_saveexec_b64 s[0:1], vcc
	s_xor_b64 s[8:9], exec, s[0:1]
	s_cbranch_execz .LBB0_1146
	s_waitcnt lgkmcnt(0)
	buffer_inv sc1
	v_mov_b32_e32 v1, 0x2000
	global_load_dword v1, v1, s[6:7] offset:1024 sc1
	s_add_u32 s12, s6, 0x2400
	s_addc_u32 s13, s7, 0
	s_waitcnt vmcnt(0)
	v_cmp_eq_u32_e32 vcc, v1, v2
	s_and_saveexec_b64 s[0:1], vcc
	s_cbranch_execz .LBB0_1145
	s_add_u32 s10, s78, 0x4200
	s_addc_u32 s11, s79, 0
	s_mov_b32 s3, 1
	s_mov_b64 s[14:15], 0
	v_mov_b32_e32 v1, 0
	global_load_dword v241, v1, s[12:13] sc1
	global_load_dword v241, v1, s[12:13] sc1
	s_branch .LBB0_1136

; __device__ __forceinline__ unsigned xb_ld(unsigned* p)              { return __hip_atomic_load(p, __ATOMIC_RELAXED, __HIP_MEMORY_SCOPE_AGENT); }
; #define XB_SPIN(cond, bar) do { unsigned _sp = 0; while (cond) { __builtin_amdgcn_s_sleep(1); \
;     if ((++_sp & 255u) == 0u) { if (xb_ld(&(bar)[XB_TMO])) break; if (_sp > XB_SPIN_CAP) { atomicAdd(&(bar)[XB_TMO], 1u); break; } } } } while (0)
; __device__ __forceinline__ void xcd_barrier(const XcdBarrier& b) {
;     ...
;             XB_SPIN(xb_ld(&bar[XB_XGEN(b.x)]) == gen, bar);
.LBB0_1140:
	global_load_dword v241, v1, s[12:13] sc1
	s_add_i32 s3, s3, 1
	s_mov_b64 s[28:29], -1
	s_waitcnt vmcnt(2)
	v_cmp_ne_u32_e32 vcc, v241, v2
	s_orn2_b64 s[26:27], vcc, exec
	s_branch .LBB0_1135

; __device__ __forceinline__ unsigned xb_ld(unsigned* p)              { return __hip_atomic_load(p, __ATOMIC_RELAXED, __HIP_MEMORY_SCOPE_AGENT); }
; __device__ __forceinline__ unsigned xb_add(unsigned* p, unsigned v) { return __hip_atomic_fetch_add(p, v, __ATOMIC_RELAXED, __HIP_MEMORY_SCOPE_AGENT); }
; #define XB_SPIN(cond, bar) do { unsigned _sp = 0; while (cond) { __builtin_amdgcn_s_sleep(1); \
;     if ((++_sp & 255u) == 0u) { if (xb_ld(&(bar)[XB_TMO])) break; if (_sp > XB_SPIN_CAP) { atomicAdd(&(bar)[XB_TMO], 1u); break; } } } } while (0)
; __device__ __forceinline__ void xcd_barrier(const XcdBarrier& b) {
;     ...
;             const unsigned og = xb_add(&bar[XB_TOP], 1u);
;             const unsigned tg = og / nx;
;             if (og + 1u == (tg + 1u) * nx) xb_add(&bar[XB_TOPGEN], 1u);
;             else XB_SPIN(xb_ld(&bar[XB_TOPGEN]) == tg, bar);
.LBB0_1149:
	s_or_b64 exec, exec, s[8:9]
	v_cvt_f32_u32_e32 v4, v1
	s_waitcnt vmcnt(0)
	v_readfirstlane_b32 s0, v3
	s_add_u32 s8, s78, 0x7500
	s_addc_u32 s9, s79, 0
	v_rcp_iflag_f32_e32 v4, v4
	v_add_u32_e32 v2, s0, v2
	v_add_u32_e32 v5, 1, v2
	s_mov_b64 s[10:11], -1
	v_mul_f32_e32 v3, 0x4f7ffffe, v4
	v_cvt_u32_f32_e32 v3, v3
	v_sub_u32_e32 v4, 0, v1
	v_mul_lo_u32 v4, v4, v3
	v_mul_hi_u32 v4, v3, v4
	v_add_u32_e32 v3, v3, v4
	v_mul_hi_u32 v3, v2, v3
	v_mul_lo_u32 v4, v3, v1
	v_sub_u32_e32 v2, v2, v4
	v_add_u32_e32 v6, 1, v3
	v_cmp_ge_u32_e32 vcc, v2, v1
	v_sub_u32_e32 v4, v2, v1
	s_nop 0
	v_cndmask_b32_e32 v3, v3, v6, vcc
	v_cndmask_b32_e32 v2, v2, v4, vcc
	v_add_u32_e32 v4, 1, v3
	v_cmp_ge_u32_e32 vcc, v2, v1
	s_nop 1
	v_cndmask_b32_e32 v4, v3, v4, vcc
	v_mul_lo_u32 v2, v1, v4
	v_add_u32_e32 v1, v2, v1
	v_cmp_ne_u32_e32 vcc, v5, v1
	v_mov_b64_e32 v[2:3], s[8:9]
	s_and_saveexec_b64 s[0:1], vcc
	s_cbranch_execz .LBB0_1161
	v_mov_b32_e32 v1, 0
	global_load_dword v2, v1, s[8:9] sc1
	s_mov_b64 s[14:15], 0
	s_waitcnt vmcnt(0)
	v_cmp_eq_u32_e32 vcc, v2, v4
	s_and_saveexec_b64 s[12:13], vcc
	s_cbranch_execz .LBB0_1160
	s_add_u32 s10, s78, 0x4200
	s_addc_u32 s11, s79, 0
	s_mov_b32 s3, 1
	global_load_dword v242, v1, s[8:9] sc1
	global_load_dword v242, v1, s[8:9] sc1
	s_branch .LBB0_1153

; __device__ __forceinline__ unsigned xb_ld(unsigned* p)              { return __hip_atomic_load(p, __ATOMIC_RELAXED, __HIP_MEMORY_SCOPE_AGENT); }
; #define XB_SPIN(cond, bar) do { unsigned _sp = 0; while (cond) { __builtin_amdgcn_s_sleep(1); \
;     if ((++_sp & 255u) == 0u) { if (xb_ld(&(bar)[XB_TMO])) break; if (_sp > XB_SPIN_CAP) { atomicAdd(&(bar)[XB_TMO], 1u); break; } } } } while (0)
; __device__ __forceinline__ void xcd_barrier(const XcdBarrier& b) {
;     ...
;             else XB_SPIN(xb_ld(&bar[XB_TOPGEN]) == tg, bar);
.LBB0_1157:
	global_load_dword v242, v1, s[8:9] sc1
	s_add_i32 s3, s3, 1
	s_mov_b64 s[26:27], -1
	s_waitcnt vmcnt(2)
	v_cmp_ne_u32_e32 vcc, v242, v4
	s_orn2_b64 s[30:31], vcc, exec
	s_branch .LBB0_1152

; __device__ __forceinline__ unsigned xb_ld(unsigned* p)              { return __hip_atomic_load(p, __ATOMIC_RELAXED, __HIP_MEMORY_SCOPE_AGENT); }
; __device__ __forceinline__ unsigned xb_add(unsigned* p, unsigned v) { return __hip_atomic_fetch_add(p, v, __ATOMIC_RELAXED, __HIP_MEMORY_SCOPE_AGENT); }
; #define XB_SPIN(cond, bar) do { unsigned _sp = 0; while (cond) { __builtin_amdgcn_s_sleep(1); \
;     if ((++_sp & 255u) == 0u) { if (xb_ld(&(bar)[XB_TMO])) break; if (_sp > XB_SPIN_CAP) { atomicAdd(&(bar)[XB_TMO], 1u); break; } } } } while (0)
; __device__ __forceinline__ void xcd_barrier(const XcdBarrier& b) {
;     ...
;         unsigned nloc = b.st[0], nx = b.st[1];
;         if (nloc == 0u) { xcd_barrier_complete(bar, b.x, nloc, nx); b.st[0] = nloc; b.st[1] = nx; }
;         const unsigned old = xb_add(&bar[XB_XSUB(b.x)], 1u);
;         const unsigned gen = old / nloc;
;         if (old + 1u == (gen + 1u) * nloc) {
;             __builtin_amdgcn_fence(__ATOMIC_RELEASE, "agent");
;             asm volatile("s_waitcnt vmcnt(0)" ::: "memory");
;             const unsigned og = xb_add(&bar[XB_TOP], 1u);
;             const unsigned tg = og / nx;
;             if (og + 1u == (tg + 1u) * nx) xb_add(&bar[XB_TOPGEN], 1u);
;             else XB_SPIN(xb_ld(&bar[XB_TOPGEN]) == tg, bar);
;             __builtin_amdgcn_fence(__ATOMIC_ACQUIRE, "agent");
;             xb_add(&bar[XB_XGEN(b.x)], 1u);
;             asm volatile("s_waitcnt vmcnt(0)" ::: "memory");
;         } else {
;             XB_SPIN(xb_ld(&bar[XB_XGEN(b.x)]) == gen, bar);
.LBB0_1204:
	s_or_b64 exec, exec, s[12:13]
	v_cvt_f32_u32_e32 v5, v3
	s_waitcnt vmcnt(0)
	v_readfirstlane_b32 s3, v4
	v_sub_u32_e32 v4, 0, v3
	v_rcp_iflag_f32_e32 v5, v5
	v_add_u32_e32 v6, s3, v2
	v_mul_f32_e32 v5, 0x4f7ffffe, v5
	v_cvt_u32_f32_e32 v5, v5
	v_mul_lo_u32 v2, v4, v5
	v_mul_hi_u32 v2, v5, v2
	v_add_u32_e32 v2, v5, v2
	v_mul_hi_u32 v2, v6, v2
	v_mul_lo_u32 v4, v2, v3
	v_sub_u32_e32 v4, v6, v4
	v_add_u32_e32 v5, 1, v2
	v_cmp_ge_u32_e32 vcc, v4, v3
	s_nop 1
	v_cndmask_b32_e32 v2, v2, v5, vcc
	v_sub_u32_e32 v5, v4, v3
	v_cndmask_b32_e32 v4, v4, v5, vcc
	v_add_u32_e32 v5, 1, v2
	v_cmp_ge_u32_e32 vcc, v4, v3
	v_add_u32_e32 v4, 1, v6
	s_nop 0
	v_cndmask_b32_e32 v2, v2, v5, vcc
	v_mul_lo_u32 v5, v3, v2
	v_add_u32_e32 v3, v5, v3
	v_cmp_ne_u32_e32 vcc, v4, v3
	s_and_saveexec_b64 s[6:7], vcc
	s_xor_b64 s[6:7], exec, s[6:7]
	s_cbranch_execz .LBB0_1218
	s_waitcnt lgkmcnt(0)
	buffer_inv sc1
	v_mov_b32_e32 v1, 0x2000
	global_load_dword v1, v1, s[0:1] offset:1024 sc1
	s_add_u32 s16, s0, 0x2400
	s_addc_u32 s17, s1, 0
	s_waitcnt vmcnt(0)
	v_cmp_eq_u32_e32 vcc, v1, v2
	s_and_saveexec_b64 s[12:13], vcc
	s_cbranch_execz .LBB0_1217
	s_add_u32 s14, s78, 0x4200
	s_addc_u32 s15, s79, 0
	s_mov_b32 s3, 1
	s_mov_b64 s[20:21], 0
	v_mov_b32_e32 v1, 0
	global_load_dword v241, v1, s[16:17] sc1
	global_load_dword v241, v1, s[16:17] sc1
	s_branch .LBB0_1208

; __device__ __forceinline__ unsigned xb_ld(unsigned* p)              { return __hip_atomic_load(p, __ATOMIC_RELAXED, __HIP_MEMORY_SCOPE_AGENT); }
; #define XB_SPIN(cond, bar) do { unsigned _sp = 0; while (cond) { __builtin_amdgcn_s_sleep(1); \
;     if ((++_sp & 255u) == 0u) { if (xb_ld(&(bar)[XB_TMO])) break; if (_sp > XB_SPIN_CAP) { atomicAdd(&(bar)[XB_TMO], 1u); break; } } } } while (0)
; __device__ __forceinline__ void xcd_barrier(const XcdBarrier& b) {
;     ...
;             XB_SPIN(xb_ld(&bar[XB_XGEN(b.x)]) == gen, bar);
.LBB0_1212:
	global_load_dword v241, v1, s[16:17] sc1
	s_add_i32 s3, s3, 1
	s_mov_b64 s[28:29], -1
	s_waitcnt vmcnt(2)
	v_cmp_ne_u32_e32 vcc, v241, v2
	s_orn2_b64 s[26:27], vcc, exec
	s_branch .LBB0_1207

; __device__ __forceinline__ unsigned xb_ld(unsigned* p)              { return __hip_atomic_load(p, __ATOMIC_RELAXED, __HIP_MEMORY_SCOPE_AGENT); }
; __device__ __forceinline__ unsigned xb_add(unsigned* p, unsigned v) { return __hip_atomic_fetch_add(p, v, __ATOMIC_RELAXED, __HIP_MEMORY_SCOPE_AGENT); }
; #define XB_SPIN(cond, bar) do { unsigned _sp = 0; while (cond) { __builtin_amdgcn_s_sleep(1); \
;     if ((++_sp & 255u) == 0u) { if (xb_ld(&(bar)[XB_TMO])) break; if (_sp > XB_SPIN_CAP) { atomicAdd(&(bar)[XB_TMO], 1u); break; } } } } while (0)
; __device__ __forceinline__ void xcd_barrier(const XcdBarrier& b) {
;     ...
;             const unsigned og = xb_add(&bar[XB_TOP], 1u);
;             const unsigned tg = og / nx;
;             if (og + 1u == (tg + 1u) * nx) xb_add(&bar[XB_TOPGEN], 1u);
;             else XB_SPIN(xb_ld(&bar[XB_TOPGEN]) == tg, bar);
.LBB0_1221:
	s_or_b64 exec, exec, s[12:13]
	v_cvt_f32_u32_e32 v4, v1
	s_waitcnt vmcnt(0)
	v_readfirstlane_b32 s3, v3
	s_add_u32 s12, s78, 0x7500
	s_addc_u32 s13, s79, 0
	v_rcp_iflag_f32_e32 v4, v4
	v_add_u32_e32 v2, s3, v2
	v_add_u32_e32 v5, 1, v2
	s_mov_b64 s[14:15], -1
	v_mul_f32_e32 v3, 0x4f7ffffe, v4
	v_cvt_u32_f32_e32 v3, v3
	v_sub_u32_e32 v4, 0, v1
	v_mul_lo_u32 v4, v4, v3
	v_mul_hi_u32 v4, v3, v4
	v_add_u32_e32 v3, v3, v4
	v_mul_hi_u32 v3, v2, v3
	v_mul_lo_u32 v4, v3, v1
	v_sub_u32_e32 v2, v2, v4
	v_add_u32_e32 v6, 1, v3
	v_cmp_ge_u32_e32 vcc, v2, v1
	v_sub_u32_e32 v4, v2, v1
	s_nop 0
	v_cndmask_b32_e32 v3, v3, v6, vcc
	v_cndmask_b32_e32 v2, v2, v4, vcc
	v_add_u32_e32 v4, 1, v3
	v_cmp_ge_u32_e32 vcc, v2, v1
	s_nop 1
	v_cndmask_b32_e32 v4, v3, v4, vcc
	v_mul_lo_u32 v2, v1, v4
	v_add_u32_e32 v1, v2, v1
	v_cmp_ne_u32_e32 vcc, v5, v1
	v_mov_b64_e32 v[2:3], s[12:13]
	s_and_saveexec_b64 s[6:7], vcc
	s_cbranch_execz .LBB0_1233
	v_mov_b32_e32 v1, 0
	global_load_dword v2, v1, s[12:13] sc1
	s_mov_b64 s[20:21], 0
	s_waitcnt vmcnt(0)
	v_cmp_eq_u32_e32 vcc, v2, v4
	s_and_saveexec_b64 s[16:17], vcc
	s_cbranch_execz .LBB0_1232
	s_add_u32 s14, s78, 0x4200
	s_addc_u32 s15, s79, 0
	s_mov_b32 s3, 1
	global_load_dword v242, v1, s[12:13] sc1
	global_load_dword v242, v1, s[12:13] sc1
	s_branch .LBB0_1225

; __device__ __forceinline__ unsigned xb_ld(unsigned* p)              { return __hip_atomic_load(p, __ATOMIC_RELAXED, __HIP_MEMORY_SCOPE_AGENT); }
; #define XB_SPIN(cond, bar) do { unsigned _sp = 0; while (cond) { __builtin_amdgcn_s_sleep(1); \
;     if ((++_sp & 255u) == 0u) { if (xb_ld(&(bar)[XB_TMO])) break; if (_sp > XB_SPIN_CAP) { atomicAdd(&(bar)[XB_TMO], 1u); break; } } } } while (0)
; __device__ __forceinline__ void xcd_barrier(const XcdBarrier& b) {
;     ...
;             else XB_SPIN(xb_ld(&bar[XB_TOPGEN]) == tg, bar);
.LBB0_1229:
	global_load_dword v242, v1, s[12:13] sc1
	s_add_i32 s3, s3, 1
	s_mov_b64 s[26:27], -1
	s_waitcnt vmcnt(2)
	v_cmp_ne_u32_e32 vcc, v242, v4
	s_orn2_b64 s[30:31], vcc, exec
	s_branch .LBB0_1224

; #define LAS __attribute__((address_space(3)))
; __global__ void __launch_bounds__(NT, 2) fwd_kernel(Args args) {
;     extern __shared__ __attribute__((aligned(16))) unsigned char lds_raw[];
;     LAS unsigned char* lds = (LAS unsigned char*)lds_raw;
	.amdhsa_kernel _Z10fwd_kernel4Args
		.amdhsa_group_segment_fixed_size 0
		.amdhsa_private_segment_fixed_size 0
		.amdhsa_kernarg_size 496
		.amdhsa_user_sgpr_count 2
		.amdhsa_user_sgpr_dispatch_ptr 0
		.amdhsa_user_sgpr_queue_ptr 0
		.amdhsa_user_sgpr_kernarg_segment_ptr 1
		.amdhsa_user_sgpr_dispatch_id 0
		.amdhsa_user_sgpr_kernarg_preload_length 0
		.amdhsa_user_sgpr_kernarg_preload_offset 0
		.amdhsa_user_sgpr_private_segment_size 0
		.amdhsa_uses_dynamic_stack 0
		.amdhsa_enable_private_segment 0
		.amdhsa_system_sgpr_workgroup_id_x 1
		.amdhsa_system_sgpr_workgroup_id_y 0
		.amdhsa_system_sgpr_workgroup_id_z 0
		.amdhsa_system_sgpr_workgroup_info 0
		.amdhsa_system_vgpr_workitem_id 0
		.amdhsa_next_free_vgpr 248
		.amdhsa_next_free_sgpr 98
		.amdhsa_accum_offset 248
		.amdhsa_reserve_vcc 1
		.amdhsa_float_round_mode_32 0
		.amdhsa_float_round_mode_16_64 0
		.amdhsa_float_denorm_mode_32 3
		.amdhsa_float_denorm_mode_16_64 3
		.amdhsa_dx10_clamp 1
		.amdhsa_ieee_mode 1
		.amdhsa_fp16_overflow 0
		.amdhsa_tg_split 0
		.amdhsa_exception_fp_ieee_invalid_op 0
		.amdhsa_exception_fp_denorm_src 0
		.amdhsa_exception_fp_ieee_div_zero 0
		.amdhsa_exception_fp_ieee_overflow 0
		.amdhsa_exception_fp_ieee_underflow 0
		.amdhsa_exception_fp_ieee_inexact 0
		.amdhsa_exception_int_div_zero 0
	.end_amdhsa_kernel

; __global__ void __launch_bounds__(NT, 2) fwd_kernel(Args args) {
;     extern __shared__ __attribute__((aligned(16))) unsigned char lds_raw[];
amdhsa.kernels:
  - .agpr_count:     0
    .args:
      - .offset:         0
        .size:           240
        .value_kind:     by_value
      - .offset:         240
        .size:           4
        .value_kind:     hidden_block_count_x
      - .offset:         244
        .size:           4
        .value_kind:     hidden_block_count_y
      - .offset:         248
        .size:           4
        .value_kind:     hidden_block_count_z
      - .offset:         252
        .size:           2
        .value_kind:     hidden_group_size_x
      - .offset:         254
        .size:           2
        .value_kind:     hidden_group_size_y
      - .offset:         256
        .size:           2
        .value_kind:     hidden_group_size_z
      - .offset:         258
        .size:           2
        .value_kind:     hidden_remainder_x
      - .offset:         260
        .size:           2
        .value_kind:     hidden_remainder_y
      - .offset:         262
        .size:           2
        .value_kind:     hidden_remainder_z
      - .offset:         280
        .size:           8
        .value_kind:     hidden_global_offset_x
      - .offset:         288
        .size:           8
        .value_kind:     hidden_global_offset_y
      - .offset:         296
        .size:           8
        .value_kind:     hidden_global_offset_z
      - .offset:         304
        .size:           2
        .value_kind:     hidden_grid_dims
      - .offset:         360
        .size:           4
        .value_kind:     hidden_dynamic_lds_size
    .group_segment_fixed_size: 0
    .kernarg_segment_align: 8
    .kernarg_segment_size: 496
    .language:       OpenCL C
    .language_version:
      - 2
      - 0
    .max_flat_workgroup_size: 512
    .name:           _Z10fwd_kernel4Args
    .private_segment_fixed_size: 0
    .sgpr_count:     104
    .sgpr_spill_count: 36
    .symbol:         _Z10fwd_kernel4Args.kd
    .uniform_work_group_size: 1
    .uses_dynamic_stack: false
    .vgpr_count:     248
    .vgpr_spill_count: 0
    .wavefront_size: 64
